# P3 attention: per-row branch-gate load hoisted from the unit epilogue to the unit prologue (both modes), so its round trip and the MODE 1 oc/bg loads overlap the walk/staging
# baseline (speedup 1.0000x reference)
; #define LAS __attribute__((address_space(3)))
; template <int MODE, int THRL>
; __device__ __forceinline__ void attn_unit(const Prm& P, int b, int h, int qb, LAS char* shm, int wid) {
;   int lane; asm volatile("v_mbcnt_lo_u32_b32 %0, -1, 0\n\tv_mbcnt_hi_u32_b32 %0, -1, %0" : "=v"(lane));
;   const int r32 = lane & 31, hi = lane >> 5;
;   const int kvh = h >> 2;
;   const long rowbase = (long)b * SEQ; const int q0 = qb * QB;
;   const int NT = MODE == 0 ? 4 * qb + 4 : (qb >= 2 ? 12 : 4 * qb + 4);
;   const int t_lo = 4 * qb + 4 - NT;
;   const bool lowband = (MODE == 1) && (NT == 12);
;   const float NEG = MODE == 0 ? -INFINITY : -1024.f;
;   const bf16_t* Qw = (const bf16_t*)(P.ws + WS_Q) + (rowbase + q0 + wid * QBLK) * QP + h * 64;
;   const bf16_t* Kh = (const bf16_t*)(P.ws + (MODE == 0 ? WS_KS : WS_KW)) + (rowbase + (long)t_lo * KVBLK) * KP + kvh * 64;
;   const bf16_t* Vh = Kh + 128;
;   const unsigned lds0 = (unsigned)(uintptr_t)shm;
;   LAS float* wsf = (LAS float*)(shm + LDS_WS + wid * WSB);
;   LAS unsigned* selp = (LAS unsigned*)(shm + LDS_WS + wid * WSB + 256) + r32;
;   const unsigned ksoff = (unsigned)(lane * KP + wid * 8) * 2u;
;   const unsigned vsoff = (unsigned)((16 * (wid & 3) + (lane >> 2)) * KP + (wid >> 2) * 32 + (lane & 3) * 8) * 2u;
;   const unsigned kdst = lds0 + LDS_K + wid * 1024, vdst = lds0 + LDS_V + wid * 1024;
;     ...
;   const int vb0 = (int)(lds0 + LDS_V) + ((lane >> 4) & 1) * 32 + (lane & 3) * 8 + (4 * hi + ((lane & 15) >> 2)) * 64;
;   bf16x8 kf[8];
;   const lds_cptr shm3 = (lds_cptr)shm; const lds_cptr kp0 = shm3 + LDS_K + hi * 1024 + r32 * 16; const lds_cptr vp0 = shm3 + LDS_V + ((lane >> 4) & 1) * 32 + (lane & 3) * 8 + (4 * hi + ((lane & 15) >> 2)) * 64;
;   DMA_K(0, 0); DMA_V(0, 0); DMA_K(1, SLOTB);
;   bf16x8 qr[4];
; #pragma unroll
;   for (int d0 = 0; d0 < 4; ++d0) qr[d0] = *(const bf16x8*)(&Qw[(long)r32 * QP + d0 * 16 + hi * 8]);
;   if (MODE == 0 && hi == 0) { const u32x4 selm = *(const u32x4*)((const unsigned*)(P.ws + WS_SELM) + ((rowbase + q0 + wid * QBLK + r32) * 2 + kvh) * 4);
;     selp[0] = selm.x; selp[32] = selm.y; selp[64] = selm.z; selp[96] = selm.w; }
;     ...
;   if (hi == 0) { const float gte = ((const float*)(P.ws + WS_G))[(row0 + r32) * 24 + h * 3 + (MODE == 0 ? 1 : 2)]; wsf[32 + r32] = l_reg > 0.f ? gte * __builtin_amdgcn_rcpf(l_reg) : 0.f; }
.LBB0_1599:
	s_ashr_i32 s0, s14, 3
	s_ashr_i32 s1, s0, 31
	s_lshl_b32 s25, s21, 8
	v_readlane_b32 s4, v251, 53
	s_and_b32 s23, s14, 7
	s_lshl_b64 s[2:3], s[0:1], 13
	s_add_i32 s4, s25, s4
	s_add_u32 s4, s2, s4
	s_addc_u32 s5, s3, 0
	s_lshl_b64 s[8:9], s[4:5], 10
	v_readlane_b32 s2, v251, 18
	v_readlane_b32 s3, v251, 19
	s_add_u32 s2, s2, s8
	s_addc_u32 s3, s3, s9
	s_lshl_b32 s6, s23, 7
	s_add_u32 s12, s2, s6
	s_addc_u32 s13, s3, 0
	s_lshl_b64 s[6:7], s[0:1], 22
	v_readlane_b32 s0, v251, 35
	s_add_u32 s0, s0, s6
	v_readlane_b32 s1, v251, 36
	s_addc_u32 s1, s1, s7
	s_lshl_b32 s2, s14, 4
	s_and_b32 s2, s2, 64
	s_waitcnt lgkmcnt(0)
	v_mbcnt_lo_u32_b32 v190, -1, 0
	v_mbcnt_hi_u32_b32 v190, -1, v190
	v_readlane_b32 s16, v251, 39
	v_readlane_b32 s17, v251, 40
	v_and_b32_e32 v241, 31, v190
	v_or_b32_e32 v241, s4, v241
	v_mul_u32_u24_e32 v241, 0x60, v241
	s_mul_i32 s18, s23, 12
	v_add_u32_e32 v241, s18, v241
	s_nop 0
	global_load_dword v240, v241, s[16:17]
	s_lshl_b32 s27, s2, 1
	v_lshrrev_b32_e32 v0, 2, v190
	s_add_u32 s2, s0, s27
	v_add_u32_e32 v0, s42, v0
	v_lshlrev_b32_e32 v2, 3, v190
	v_ashrrev_i32_e32 v189, 5, v190
	s_addc_u32 s3, s1, 0
	v_lshl_add_u32 v0, v0, 8, s43
	v_and_b32_e32 v191, 24, v2
	s_add_u32 s10, s2, 0x100
	v_lshl_add_u32 v197, v190, 9, s41
	v_or_b32_e32 v0, v0, v191
	s_mov_b32 s0, m0
	s_mov_b32 m0, s44
	s_nop 0
	global_load_lds_dwordx4 v197, s[2:3]
	s_mov_b32 m0, s0
	v_lshlrev_b32_e32 v2, 3, v189
	v_and_b32_e32 v188, 31, v190
	s_addc_u32 s11, s3, 0
	v_lshlrev_b32_e32 v198, 1, v0
	s_mov_b32 s0, m0
	s_mov_b32 m0, s45
	s_nop 0
	global_load_lds_dwordx4 v198, s[10:11]
	s_mov_b32 m0, s0
	v_ashrrev_i32_e32 v3, 31, v2
	s_add_u32 s0, s2, 0x8000
	v_lshl_add_u64 v[2:3], v[2:3], 1, s[12:13]
	v_lshlrev_b32_e32 v0, 10, v188
	s_addc_u32 s1, s3, 0
	s_add_i32 s26, s44, 0x2000
	s_mov_b32 s15, m0
	s_mov_b32 m0, s26
	s_nop 0
	global_load_lds_dwordx4 v197, s[0:1]
	s_mov_b32 m0, s15
	v_lshl_add_u64 v[2:3], v[2:3], 0, v[0:1]
	global_load_dwordx4 v[136:139], v[2:3], off
	global_load_dwordx4 v[128:131], v[2:3], off offset:32
	global_load_dwordx4 v[116:119], v[2:3], off offset:64
	global_load_dwordx4 v[112:115], v[2:3], off offset:96
	v_lshl_add_u32 v194, v188, 2, s40
	v_cmp_gt_u32_e64 s[0:1], 32, v190
	s_and_saveexec_b64 s[12:13], s[0:1]
	s_cbranch_execz .LBB0_1601
	v_or_b32_e32 v2, s4, v190
	v_mov_b32_e32 v3, s5
	v_readlane_b32 s16, v251, 37
	s_and_b32 s14, s14, 4
	v_lshlrev_b64 v[2:3], 5, v[2:3]
	v_readlane_b32 s17, v251, 38
	s_lshl_b32 s78, s14, 2
	v_add_u32_e32 v0, 0xc000, v194
	v_lshl_add_u64 v[2:3], s[16:17], 0, v[2:3]
	v_lshl_add_u64 v[2:3], v[2:3], 0, s[78:79]
	global_load_dwordx4 v[2:5], v[2:3], off
	s_waitcnt vmcnt(0)
	ds_write2_b32 v0, v2, v3 offset0:64 offset1:96
	ds_write2_b32 v0, v4, v5 offset0:128 offset1:160

; #define LAS __attribute__((address_space(3)))
; __device__ __forceinline__ unsigned f2bf(float f) { unsigned u = __builtin_bit_cast(unsigned, f); return (u + 0x7fffu + ((u >> 16) & 1u)) >> 16; }
; __device__ __forceinline__ int crow(int r, int hi) { return (r & 3) + 8 * (r >> 2) + 4 * hi; }
; #define SBAR() __builtin_amdgcn_sched_barrier(0)
; #define PKW(P, B) cvtpk_s(P[B], P[B + 1])
; template <int MODE, int THRL>
; __device__ __forceinline__ void attn_unit(const Prm& P, int b, int h, int qb, LAS char* shm, int wid) {
;     ...
;   { float sacc = pB0[0] + pB0[1];
; #pragma unroll
;     for (int r = 2; r < 16; ++r) sacc += pB0[r];
; #pragma unroll
;     for (int r = 0; r < 16; ++r) sacc += pB1[r];
;     l_reg += sacc;
;     pw0 = (u32x4){PKW(pB0, 0), PKW(pB0, 2), PKW(pB0, 4), PKW(pB0, 6)}; pw1 = (u32x4){PKW(pB0, 8), PKW(pB0, 10), PKW(pB0, 12), PKW(pB0, 14)};
;     pw2 = (u32x4){PKW(pB1, 0), PKW(pB1, 2), PKW(pB1, 4), PKW(pB1, 6)}; pw3 = (u32x4){PKW(pB1, 8), PKW(pB1, 10), PKW(pB1, 12), PKW(pB1, 14)};
;     SBAR(); pv(o, vb0 + sl_cur, PAF(0), PAF(1), PAF(2), PAF(3)); }
;     ...
;   { auto rr = __builtin_amdgcn_permlane32_swap(__float_as_uint(l_reg), __float_as_uint(l_reg), false, false); l_reg = __uint_as_float(rr[0]) + __uint_as_float(rr[1]); }
;     ...
;   if (hi == 0) { const float gte = ((const float*)(P.ws + WS_G))[(row0 + r32) * 24 + h * 3 + (MODE == 0 ? 1 : 2)]; wsf[32 + r32] = l_reg > 0.f ? gte * __builtin_amdgcn_rcpf(l_reg) : 0.f; }
;   asm volatile("s_waitcnt lgkmcnt(0)" ::: "memory");
;   float rli[16];
; #pragma unroll
;   for (int r = 0; r < 16; ++r) rli[r] = wsf[32 + crow(r, hi)];
;   { LAS bf16_t* stg = (LAS bf16_t*)(shm + (MODE == 0 ? LDS_OS2 : LDS_OST)) + wid * 2048;
; #pragma unroll
;     for (int r = 0; r < 16; ++r) { const int orow = crow(r, hi);
; #pragma unroll
;       for (int d0 = 0; d0 < 2; ++d0) stg[orow * 64 + d0 * 32 + r32] = (bf16_t)f2bf(o[d0][r] * rli[r]); }
.LBB0_1677:
	v_add_f32_e32 v4, v96, v97
	v_add_f32_e32 v4, v98, v4
	v_add_f32_e32 v4, v99, v4
	v_add_f32_e32 v4, v100, v4
	v_add_f32_e32 v4, v101, v4
	v_add_f32_e32 v4, v102, v4
	v_add_f32_e32 v4, v103, v4
	v_add_f32_e32 v4, v104, v4
	v_add_f32_e32 v4, v105, v4
	v_add_f32_e32 v4, v106, v4
	v_add_f32_e32 v4, v107, v4
	v_add_f32_e32 v4, v108, v4
	v_add_f32_e32 v4, v109, v4
	v_add_f32_e32 v4, v110, v4
	v_add_f32_e32 v4, v111, v4
	v_add_f32_e32 v4, v80, v4
	v_add_f32_e32 v4, v81, v4
	v_add_f32_e32 v4, v82, v4
	v_add_f32_e32 v4, v83, v4
	v_add_f32_e32 v4, v84, v4
	v_add_f32_e32 v4, v85, v4
	v_add_f32_e32 v4, v86, v4
	v_add_f32_e32 v4, v87, v4
	v_add_f32_e32 v4, v88, v4
	v_add_f32_e32 v4, v89, v4
	v_add_f32_e32 v4, v90, v4
	v_add_f32_e32 v4, v91, v4
	v_add_f32_e32 v4, v92, v4
	v_add_f32_e32 v4, v93, v4
	v_add_f32_e32 v4, v94, v4
	s_add_i32 s25, 0, 0x6000
	v_add_f32_e32 v4, v95, v4
	v_add3_u32 v3, v193, s25, v191
	v_add_f32_e32 v0, v0, v4
	v_cvt_pk_bf16_f32 v4, v96, v97
	v_cvt_pk_bf16_f32 v5, v98, v99
	v_cvt_pk_bf16_f32 v6, v100, v101
	v_cvt_pk_bf16_f32 v7, v102, v103
	v_cvt_pk_bf16_f32 v8, v104, v105
	v_cvt_pk_bf16_f32 v9, v106, v107
	v_cvt_pk_bf16_f32 v10, v108, v109
	v_cvt_pk_bf16_f32 v11, v110, v111
	v_cvt_pk_bf16_f32 v12, v80, v81
	v_cvt_pk_bf16_f32 v13, v82, v83
	v_cvt_pk_bf16_f32 v14, v84, v85
	v_cvt_pk_bf16_f32 v15, v86, v87
	v_cvt_pk_bf16_f32 v48, v88, v89
	v_cvt_pk_bf16_f32 v49, v90, v91
	v_cvt_pk_bf16_f32 v50, v92, v93
	v_cvt_pk_bf16_f32 v51, v94, v95
	v_add3_u32 v3, v3, v192, s29
	ds_read_b64_tr_b16 v[52:53],v3 offset:0
	ds_read_b64_tr_b16 v[54:55],v3 offset:512
	ds_read_b64_tr_b16 v[56:57],v3 offset:1024
	ds_read_b64_tr_b16 v[58:59],v3 offset:1536
	ds_read_b64_tr_b16 v[60:61],v3 offset:2048
	ds_read_b64_tr_b16 v[62:63],v3 offset:2560
	ds_read_b64_tr_b16 v[64:65],v3 offset:3072
	ds_read_b64_tr_b16 v[66:67],v3 offset:3584
	s_waitcnt lgkmcnt(0)
	s_nop 0
	v_mfma_f32_32x32x16_bf16 v[32:47], v[4:7], v[52:55], v[32:47]
	ds_read_b64_tr_b16 v[52:53],v3 offset:4096
	ds_read_b64_tr_b16 v[54:55],v3 offset:4608
	v_mfma_f32_32x32x16_bf16 v[32:47], v[8:11], v[56:59], v[32:47]
	ds_read_b64_tr_b16 v[56:57],v3 offset:5120
	ds_read_b64_tr_b16 v[58:59],v3 offset:5632
	v_mfma_f32_32x32x16_bf16 v[32:47], v[12:15], v[60:63], v[32:47]
	ds_read_b64_tr_b16 v[60:61],v3 offset:6144
	ds_read_b64_tr_b16 v[62:63],v3 offset:6656
	v_mfma_f32_32x32x16_bf16 v[32:47], v[48:51], v[64:67], v[32:47]
	ds_read_b64_tr_b16 v[64:65],v3 offset:7168
	ds_read_b64_tr_b16 v[66:67],v3 offset:7680
	s_waitcnt lgkmcnt(0)
	v_mfma_f32_32x32x16_bf16 v[16:31], v[4:7], v[52:55], v[16:31]
	v_mov_b32_e32 v3, v0
	s_nop 1
	v_permlane32_swap_b32_e32 v0, v3
	v_mov_b32_e32 v4, v190
	v_mfma_f32_32x32x16_bf16 v[16:31], v[8:11], v[56:59], v[16:31]
	v_mfma_f32_32x32x16_bf16 v[16:31], v[12:15], v[60:63], v[16:31]
	v_mfma_f32_32x32x16_bf16 v[16:31], v[48:51], v[64:67], v[16:31]
	s_and_saveexec_b64 s[2:3], s[0:1]
	s_cbranch_execz .LBB0_1679
	v_add_f32_e32 v0, v0, v3
	s_mul_i32 s78, s23, 12
	v_cmp_lt_f32_e32 vcc, 0, v0
	v_rcp_f32_e32 v0, v0
	s_nop 0
	v_mul_f32_e32 v0, v0, v240
	v_cndmask_b32_e32 v0, 0, v0, vcc
	v_lshl_add_u32 v3, v190, 2, s40
	ds_write_b32 v3, v0 offset:49280
.LBB0_1679:
	s_or_b64 exec, exec, s[2:3]
	s_waitcnt lgkmcnt(0)
	ds_read_b128 v[4:7], v2 offset:49280
	ds_read_b128 v[8:11], v2 offset:49312
	ds_read_b128 v[12:15], v2 offset:49344
	ds_read_b128 v[48:51], v2 offset:49376
	v_lshlrev_b32_e32 v0, 9, v189
	v_lshlrev_b32_e32 v2, 1, v188
	v_add3_u32 v0, s46, v0, v2
	s_waitcnt lgkmcnt(3)
	v_mul_f32_e32 v2, v32, v4
	s_movk_i32 s0, 0x7fff
	v_cvt_pk_bf16_f32 v2, v2, v2
	ds_write_b16_d16_hi v0, v2
	v_mul_f32_e32 v2, v16, v4
	v_cvt_pk_bf16_f32 v2, v2, v2
	ds_write_b16_d16_hi v0, v2 offset:64
	v_mul_f32_e32 v2, v33, v5
	v_cvt_pk_bf16_f32 v2, v2, v2
	ds_write_b16_d16_hi v0, v2 offset:128
	v_mul_f32_e32 v2, v17, v5
	v_cvt_pk_bf16_f32 v2, v2, v2
	ds_write_b16_d16_hi v0, v2 offset:192
	v_mul_f32_e32 v2, v34, v6
	v_cvt_pk_bf16_f32 v2, v2, v2
	ds_write_b16_d16_hi v0, v2 offset:256
	v_mul_f32_e32 v2, v18, v6
	v_cvt_pk_bf16_f32 v2, v2, v2
	ds_write_b16_d16_hi v0, v2 offset:320
	v_mul_f32_e32 v2, v35, v7
	v_cvt_pk_bf16_f32 v2, v2, v2
	ds_write_b16_d16_hi v0, v2 offset:384
	v_mul_f32_e32 v2, v19, v7
	v_cvt_pk_bf16_f32 v2, v2, v2
	ds_write_b16_d16_hi v0, v2 offset:448
	s_waitcnt lgkmcnt(10)
	v_mul_f32_e32 v2, v36, v8
	v_cvt_pk_bf16_f32 v2, v2, v2
	ds_write_b16_d16_hi v0, v2 offset:1024
	v_mul_f32_e32 v2, v20, v8
	v_cvt_pk_bf16_f32 v2, v2, v2
	ds_write_b16_d16_hi v0, v2 offset:1088
	v_mul_f32_e32 v2, v37, v9
	v_cvt_pk_bf16_f32 v2, v2, v2
	ds_write_b16_d16_hi v0, v2 offset:1152
	v_mul_f32_e32 v2, v21, v9
	v_cvt_pk_bf16_f32 v2, v2, v2
	ds_write_b16_d16_hi v0, v2 offset:1216
	v_mul_f32_e32 v2, v38, v10
	v_cvt_pk_bf16_f32 v2, v2, v2
	ds_write_b16_d16_hi v0, v2 offset:1280
	v_mul_f32_e32 v2, v22, v10
	v_cvt_pk_bf16_f32 v2, v2, v2
	ds_write_b16_d16_hi v0, v2 offset:1344
	v_mul_f32_e32 v2, v39, v11
	v_cvt_pk_bf16_f32 v2, v2, v2
	ds_write_b16_d16_hi v0, v2 offset:1408
	v_mul_f32_e32 v2, v23, v11
	v_cvt_pk_bf16_f32 v2, v2, v2
	ds_write_b16_d16_hi v0, v2 offset:1472
	s_waitcnt lgkmcnt(14)
; template <int MODE, int THRL>
; __device__ __forceinline__ void attn_unit(const Prm& P, int b, int h, int qb, LAS char* shm, int wid) {
;   int lane; asm volatile("v_mbcnt_lo_u32_b32 %0, -1, 0\n\tv_mbcnt_hi_u32_b32 %0, -1, %0" : "=v"(lane));
;   const int r32 = lane & 31, hi = lane >> 5;
;   const int kvh = h >> 2;
;   const long rowbase = (long)b * SEQ; const int q0 = qb * QB;
;   const int NT = MODE == 0 ? 4 * qb + 4 : (qb >= 2 ? 12 : 4 * qb + 4);
;   const int t_lo = 4 * qb + 4 - NT;
;   const bool lowband = (MODE == 1) && (NT == 12);
;   const float NEG = MODE == 0 ? -INFINITY : -1024.f;
;   const bf16_t* Qw = (const bf16_t*)(P.ws + WS_Q) + (rowbase + q0 + wid * QBLK) * QP + h * 64;
;   const bf16_t* Kh = (const bf16_t*)(P.ws + (MODE == 0 ? WS_KS : WS_KW)) + (rowbase + (long)t_lo * KVBLK) * KP + kvh * 64;
;   const bf16_t* Vh = Kh + 128;
;   const unsigned lds0 = (unsigned)(uintptr_t)shm;
;   LAS float* wsf = (LAS float*)(shm + LDS_WS + wid * WSB);
;   LAS unsigned* selp = (LAS unsigned*)(shm + LDS_WS + wid * WSB + 256) + r32;
;   const unsigned ksoff = (unsigned)(lane * KP + wid * 8) * 2u;
;   const unsigned vsoff = (unsigned)((16 * (wid & 3) + (lane >> 2)) * KP + (wid >> 2) * 32 + (lane & 3) * 8) * 2u;
;   const unsigned kdst = lds0 + LDS_K + wid * 1024, vdst = lds0 + LDS_V + wid * 1024;
;     ...
;   const int vb0 = (int)(lds0 + LDS_V) + ((lane >> 4) & 1) * 32 + (lane & 3) * 8 + (4 * hi + ((lane & 15) >> 2)) * 64;
;   bf16x8 kf[8];
;   const lds_cptr shm3 = (lds_cptr)shm; const lds_cptr kp0 = shm3 + LDS_K + hi * 1024 + r32 * 16; const lds_cptr vp0 = shm3 + LDS_V + ((lane >> 4) & 1) * 32 + (lane & 3) * 8 + (4 * hi + ((lane & 15) >> 2)) * 64;
;   DMA_K(0, 0); DMA_V(0, 0); DMA_K(1, SLOTB);
;   bf16x8 qr[4];
; #pragma unroll
;   for (int d0 = 0; d0 < 4; ++d0) qr[d0] = *(const bf16x8*)(&Qw[(long)r32 * QP + d0 * 16 + hi * 8]);
;   if (MODE == 0 && hi == 0) { const u32x4 selm = *(const u32x4*)((const unsigned*)(P.ws + WS_SELM) + ((rowbase + q0 + wid * QBLK + r32) * 2 + kvh) * 4);
;     selp[0] = selm.x; selp[32] = selm.y; selp[64] = selm.z; selp[96] = selm.w; }
;     ...
;     for (int r = 0; r < 16; ++r) { const int orow = crow(r, hi);
; #pragma unroll
;       for (int d0 = 0; d0 < 2; ++d0) stg[orow * 64 + d0 * 32 + r32] = (bf16_t)f2bf(o[d0][r] * rli[r]); }
;     ...
;   asm volatile("s_waitcnt vmcnt(0) lgkmcnt(0)\n\ts_barrier" ::: "memory");
	v_mul_f32_e32 v2, v40, v12
	v_cvt_pk_bf16_f32 v2, v2, v2
	ds_write_b16_d16_hi v0, v2 offset:2048
	v_mul_f32_e32 v2, v24, v12
	v_cvt_pk_bf16_f32 v2, v2, v2
	ds_write_b16_d16_hi v0, v2 offset:2112
	v_mul_f32_e32 v2, v41, v13
	v_cvt_pk_bf16_f32 v2, v2, v2
	ds_write_b16_d16_hi v0, v2 offset:2176
	v_mul_f32_e32 v2, v25, v13
	v_cvt_pk_bf16_f32 v2, v2, v2
	ds_write_b16_d16_hi v0, v2 offset:2240
	v_mul_f32_e32 v2, v42, v14
	v_cvt_pk_bf16_f32 v2, v2, v2
	ds_write_b16_d16_hi v0, v2 offset:2304
	v_mul_f32_e32 v2, v26, v14
	v_cvt_pk_bf16_f32 v2, v2, v2
	ds_write_b16_d16_hi v0, v2 offset:2368
	v_mul_f32_e32 v2, v43, v15
	v_cvt_pk_bf16_f32 v2, v2, v2
	ds_write_b16_d16_hi v0, v2 offset:2432
	v_mul_f32_e32 v2, v27, v15
	v_cvt_pk_bf16_f32 v2, v2, v2
	ds_write_b16_d16_hi v0, v2 offset:2496
	v_mul_f32_e32 v2, v44, v48
	v_cvt_pk_bf16_f32 v2, v2, v2
	ds_write_b16_d16_hi v0, v2 offset:3072
	v_mul_f32_e32 v2, v28, v48
	v_cvt_pk_bf16_f32 v2, v2, v2
	ds_write_b16_d16_hi v0, v2 offset:3136
	v_mul_f32_e32 v2, v45, v49
	v_cvt_pk_bf16_f32 v2, v2, v2
	ds_write_b16_d16_hi v0, v2 offset:3200
	v_mul_f32_e32 v2, v29, v49
	v_cvt_pk_bf16_f32 v2, v2, v2
	ds_write_b16_d16_hi v0, v2 offset:3264
	v_mul_f32_e32 v2, v46, v50
	v_cvt_pk_bf16_f32 v2, v2, v2
	ds_write_b16_d16_hi v0, v2 offset:3328
	v_mul_f32_e32 v2, v30, v50
	v_cvt_pk_bf16_f32 v2, v2, v2
	ds_write_b16_d16_hi v0, v2 offset:3392
	v_mul_f32_e32 v2, v47, v51
	v_cvt_pk_bf16_f32 v2, v2, v2
	ds_write_b16_d16_hi v0, v2 offset:3456
	v_mul_f32_e32 v2, v31, v51
	s_cmp_lt_i32 s21, 2
	s_cselect_b32 s29, s31, 12
	v_cvt_pk_bf16_f32 v2, v2, v2
	s_sub_i32 s0, s31, s29
	v_readlane_b32 s2, v251, 18
	v_readlane_b32 s3, v251, 19
	s_add_u32 s1, s2, s8
	s_addc_u32 s2, s3, s9
	s_lshl_b32 s24, s30, 1
	s_add_u32 s8, s1, s24
	s_addc_u32 s9, s2, 0
	s_ashr_i32 s1, s0, 31
	s_lshl_b64 s[0:1], s[0:1], 15
	v_readlane_b32 s2, v251, 41
	s_add_u32 s0, s2, s0
	v_readlane_b32 s2, v251, 42
	ds_write_b16_d16_hi v0, v2 offset:3520
	s_addc_u32 s1, s2, s1
	s_waitcnt lgkmcnt(0)
	s_add_u32 s0, s0, s6
	s_waitcnt vmcnt(0) lgkmcnt(0)
	s_barrier
	v_mbcnt_lo_u32_b32 v208, -1, 0
	v_mbcnt_hi_u32_b32 v208, -1, v208
	v_readlane_b32 s16, v251, 45
	v_readlane_b32 s17, v251, 46
	v_and_b32_e32 v241, 31, v208
	v_or_b32_e32 v241, s4, v241
	v_mul_u32_u24_e32 v241, 0x60, v241
	s_mul_i32 s18, s23, 12
	v_add_u32_e32 v241, s18, v241
	s_nop 0
	global_load_dword v240, v241, s[16:17]
	s_addc_u32 s1, s1, s7
	v_lshrrev_b32_e32 v0, 2, v208
	s_add_u32 s2, s0, s27
	v_add_u32_e32 v0, s42, v0
	v_lshlrev_b32_e32 v2, 3, v208
	v_ashrrev_i32_e32 v206, 5, v208
	s_addc_u32 s3, s1, 0
	v_lshl_add_u32 v0, v0, 8, s43
	v_and_b32_e32 v210, 24, v2
	s_add_u32 s10, s2, 0x100
	v_lshl_add_u32 v220, v208, 9, s41
	v_or_b32_e32 v0, v0, v210
	s_mov_b32 s0, m0
	s_mov_b32 m0, s44
	s_nop 0
	global_load_lds_dwordx4 v220, s[2:3]
	s_mov_b32 m0, s0
	v_lshlrev_b32_e32 v2, 3, v206
	v_and_b32_e32 v204, 31, v208
	s_addc_u32 s11, s3, 0
	v_lshlrev_b32_e32 v222, 1, v0
	s_mov_b32 s0, m0
	s_mov_b32 m0, s45
	s_nop 0
	global_load_lds_dwordx4 v222, s[10:11]
	s_mov_b32 m0, s0
	v_ashrrev_i32_e32 v3, 31, v2
	s_add_u32 s0, s2, 0x8000
	v_lshl_add_u64 v[2:3], v[2:3], 1, s[8:9]
	v_lshlrev_b32_e32 v0, 10, v204
	s_addc_u32 s1, s3, 0
	s_mov_b32 s6, m0
	s_mov_b32 m0, s26
	s_nop 0
	global_load_lds_dwordx4 v220, s[0:1]
	s_mov_b32 m0, s6
	v_lshl_add_u64 v[2:3], v[2:3], 0, v[0:1]
	global_load_dwordx4 v[140:143], v[2:3], off
	global_load_dwordx4 v[136:139], v[2:3], off offset:32
	global_load_dwordx4 v[132:135], v[2:3], off offset:64
	global_load_dwordx4 v[128:131], v[2:3], off offset:96
	v_lshlrev_b32_e32 v0, 10, v206
	v_lshlrev_b32_e32 v4, 4, v204
	v_add3_u32 v226, 0, v0, v4
	v_mov_b32_e32 v2, v1
	v_mov_b32_e32 v3, v1
	v_mov_b32_e32 v4, v1
	v_mov_b32_e32 v5, v1
	v_mov_b32_e32 v6, v1
	v_mov_b32_e32 v7, v1
	v_mov_b32_e32 v8, v1
	v_mov_b32_e32 v9, v1
	v_mov_b32_e32 v10, v1
	v_mov_b32_e32 v11, v1
	v_mov_b32_e32 v12, v1
	v_mov_b32_e32 v13, v1
	v_mov_b32_e32 v14, v1
	v_mov_b32_e32 v15, v1
	v_mov_b32_e32 v0, v1
	v_mov_b64_e32 v[16:17], v[14:15]
	v_mov_b64_e32 v[14:15], v[12:13]
	v_mov_b64_e32 v[12:13], v[10:11]
	v_mov_b64_e32 v[10:11], v[8:9]
	v_mov_b64_e32 v[8:9], v[6:7]
	v_mov_b64_e32 v[6:7], v[4:5]
	v_mov_b64_e32 v[4:5], v[2:3]
	v_mov_b64_e32 v[2:3], v[0:1]
	s_add_u32 s0, s2, 0x10000
	s_addc_u32 s1, s3, 0
	s_mov_b32 s6, m0
	s_mov_b32 m0, s28
	s_nop 0
	global_load_lds_dwordx4 v220, s[0:1]
	s_mov_b32 m0, s6
	s_waitcnt vmcnt(3) lgkmcnt(0)
	s_barrier
; #define LAS __attribute__((address_space(3)))
; #define MFMA32(a, b, c) __builtin_amdgcn_mfma_f32_32x32x16_bf16((a), (b), (c), 0, 0, 0)
; #define CMASK(P0, P1, t) do { int jb_ = (t) - (NT - 4); if (jb_ >= 0) cmask(P0, P1, jb_, qrel, hi, NEG); if (lowband && (t) < 4) lmask(P0, P1, (t), qrel, hi, NEG); } while (0)
; #define CMASK(P0, P1, t) do { if (lowband && (t) < 4) lmask(P0, P1, (t), qrel, hi, NEG); } while (0)
; #define CMASK(P0, P1, t) do { int jb_ = (t) - (NT - 4); if (jb_ >= 0) cmask(P0, P1, jb_, qrel, hi, NEG); if (lowband && (t) < 4) lmask(P0, P1, (t), qrel, hi, NEG); } while (0)
; __device__ __forceinline__ void cmask(f32x16& p0, f32x16& p1, int jb, int qrel, int hi, float NEG) {
;   asm volatile("" : "+v"(qrel));
;   const int kb = 64 * jb + 4 * hi;
; #pragma unroll
;   for (int r = 0; r < 16; ++r) { const int kv = kb + (r & 3) + 8 * (r >> 2); if (kv > qrel) p0[r] = NEG; if (kv + 32 > qrel) p1[r] = NEG; }
; }
; template <int MODE, int THRL>
; __device__ __forceinline__ void attn_unit(const Prm& P, int b, int h, int qb, LAS char* shm, int wid) {
;     ...
;   {
;     const lds_cptr kb = shm3 + LDS_K + hi * 1024 + r32 * 16;
; #pragma unroll
;     for (int d0 = 0; d0 < 4; ++d0) {
;       const bf16x8 b0 = *(const LAS bf16x8*)(kb + d0 * 2048), b1 = *(const LAS bf16x8*)(kb + d0 * 2048 + 512);
;       if (d0 == 0) { pA0 = MFMA32(b0, qr[0], negm); pA1 = MFMA32(b1, qr[0], negm); }
;       else { pA0 = MFMA32(b0, qr[d0], pA0); pA1 = MFMA32(b1, qr[d0], pA1); } }
;   }
;   asm volatile("s_nop 15\n\ts_nop 7" : "+v"(pA0), "+v"(pA1)); CMASK(pA0, pA1, 0);
	ds_read_b128 v[34:37], v226
	s_waitcnt vmcnt(3) lgkmcnt(0)
	v_mfma_f32_32x32x16_bf16 v[18:33], v[34:37], v[140:143], v[2:17]
	ds_read_b128 v[34:37], v226 offset:512
	v_readlane_b32 s0, v251, 53
	s_cmp_gt_u32 s29, 4
	s_nop 0
	v_or_b32_e32 v218, s0, v204
	s_waitcnt lgkmcnt(0)
	v_mfma_f32_32x32x16_bf16 v[2:17], v[34:37], v[140:143], v[2:17]
	ds_read_b128 v[34:37], v226 offset:2048
	s_waitcnt vmcnt(2) lgkmcnt(0)
	v_mfma_f32_32x32x16_bf16 v[18:33], v[34:37], v[136:139], v[18:33]
	ds_read_b128 v[34:37], v226 offset:2560
	s_waitcnt lgkmcnt(0)
	v_mfma_f32_32x32x16_bf16 v[2:17], v[34:37], v[136:139], v[2:17]
	ds_read_b128 v[34:37], v226 offset:4096
	s_waitcnt vmcnt(1) lgkmcnt(0)
	v_mfma_f32_32x32x16_bf16 v[18:33], v[34:37], v[132:135], v[18:33]
	ds_read_b128 v[34:37], v226 offset:4608
	s_waitcnt lgkmcnt(0)
	v_mfma_f32_32x32x16_bf16 v[2:17], v[34:37], v[132:135], v[2:17]
	ds_read_b128 v[34:37], v226 offset:6144
	s_waitcnt vmcnt(0) lgkmcnt(0)
	v_mfma_f32_32x32x16_bf16 v[18:33], v[34:37], v[128:131], v[18:33]
	ds_read_b128 v[34:37], v226 offset:6656
	s_waitcnt lgkmcnt(0)
	v_mfma_f32_32x32x16_bf16 v[2:17], v[34:37], v[128:131], v[2:17]
	s_nop 15
	s_nop 7
	s_cbranch_scc1 .LBB0_1681
	v_lshlrev_b32_e32 v34, 2, v206
	v_mov_b32_e32 v0, v218
	v_add_u32_e32 v35, 32, v34
	s_nop 0
	v_cmp_le_i32_e32 vcc, v35, v0
	v_add_u32_e32 v35, 33, v34
	s_nop 4
	v_cndmask_b32_e32 v2, v219, v2, vcc
	v_cmp_lt_i32_e32 vcc, v34, v0
	s_nop 1
	v_cndmask_b32_e32 v19, v219, v19, vcc
	v_cmp_le_i32_e32 vcc, v34, v0
	s_nop 1
	v_cndmask_b32_e32 v18, v219, v18, vcc
	v_cmp_le_i32_e32 vcc, v35, v0
	v_or_b32_e32 v35, 2, v34
	s_nop 0
	v_cndmask_b32_e32 v3, v219, v3, vcc
	v_cmp_le_i32_e32 vcc, v35, v0
	v_add_u32_e32 v35, 34, v34
	s_nop 0
	v_cndmask_b32_e32 v20, v219, v20, vcc
	v_cmp_le_i32_e32 vcc, v35, v0
	v_or_b32_e32 v35, 3, v34
	s_nop 0
	v_cndmask_b32_e32 v4, v219, v4, vcc
	v_cmp_le_i32_e32 vcc, v35, v0
	v_add_u32_e32 v35, 35, v34
	s_nop 0
	v_cndmask_b32_e32 v21, v219, v21, vcc
	v_cmp_le_i32_e32 vcc, v35, v0
	v_add_u32_e32 v35, 8, v34
	s_nop 0
	v_cndmask_b32_e32 v5, v219, v5, vcc
	v_cmp_le_i32_e32 vcc, v35, v0
	v_add_u32_e32 v35, 40, v34
	s_nop 0
	v_cndmask_b32_e32 v22, v219, v22, vcc
	v_cmp_le_i32_e32 vcc, v35, v0
	v_add_u32_e32 v35, 9, v34
	s_nop 0
	v_cndmask_b32_e32 v6, v219, v6, vcc
	v_cmp_le_i32_e32 vcc, v35, v0
	v_add_u32_e32 v35, 41, v34
	s_nop 0
	v_cndmask_b32_e32 v23, v219, v23, vcc
	v_cmp_le_i32_e32 vcc, v35, v0
	v_add_u32_e32 v35, 10, v34
	s_nop 0
	v_cndmask_b32_e32 v7, v219, v7, vcc
	v_cmp_le_i32_e32 vcc, v35, v0
	v_add_u32_e32 v35, 42, v34
	s_nop 0
	v_cndmask_b32_e32 v24, v219, v24, vcc
	v_cmp_le_i32_e32 vcc, v35, v0
	v_add_u32_e32 v35, 11, v34
	s_nop 0
	v_cndmask_b32_e32 v8, v219, v8, vcc
	v_cmp_le_i32_e32 vcc, v35, v0
	v_add_u32_e32 v35, 43, v34
	s_nop 0
	v_cndmask_b32_e32 v25, v219, v25, vcc
	v_cmp_le_i32_e32 vcc, v35, v0
	v_add_u32_e32 v35, 16, v34
	s_nop 0
	v_cndmask_b32_e32 v9, v219, v9, vcc
	v_cmp_le_i32_e32 vcc, v35, v0
	v_add_u32_e32 v35, 48, v34
	s_nop 0
	v_cndmask_b32_e32 v26, v219, v26, vcc
	v_cmp_le_i32_e32 vcc, v35, v0
	v_add_u32_e32 v35, 17, v34
	s_nop 0
	v_cndmask_b32_e32 v10, v219, v10, vcc
	v_cmp_le_i32_e32 vcc, v35, v0
	v_add_u32_e32 v35, 49, v34
	s_nop 0
	v_cndmask_b32_e32 v27, v219, v27, vcc
	v_cmp_le_i32_e32 vcc, v35, v0
	v_add_u32_e32 v35, 18, v34
	s_nop 0
	v_cndmask_b32_e32 v11, v219, v11, vcc
	v_cmp_le_i32_e32 vcc, v35, v0
	v_add_u32_e32 v35, 50, v34
	s_nop 0
	v_cndmask_b32_e32 v28, v219, v28, vcc
	v_cmp_le_i32_e32 vcc, v35, v0
	v_add_u32_e32 v35, 19, v34
	s_nop 0
	v_cndmask_b32_e32 v12, v219, v12, vcc
	v_cmp_le_i32_e32 vcc, v35, v0
	v_add_u32_e32 v35, 51, v34
	s_nop 0
	v_cndmask_b32_e32 v29, v219, v29, vcc
	v_cmp_le_i32_e32 vcc, v35, v0
	v_add_u32_e32 v35, 24, v34
	s_nop 0
	v_cndmask_b32_e32 v13, v219, v13, vcc
	v_cmp_le_i32_e32 vcc, v35, v0
	v_add_u32_e32 v35, 56, v34
	s_nop 0
	v_cndmask_b32_e32 v30, v219, v30, vcc
	v_cmp_le_i32_e32 vcc, v35, v0
	v_add_u32_e32 v35, 25, v34
	s_nop 0
	v_cndmask_b32_e32 v14, v219, v14, vcc
	v_cmp_le_i32_e32 vcc, v35, v0
	v_add_u32_e32 v35, 57, v34
	s_nop 0
	v_cndmask_b32_e32 v31, v219, v31, vcc
	v_cmp_le_i32_e32 vcc, v35, v0
	v_add_u32_e32 v35, 26, v34
	s_nop 0
	v_cndmask_b32_e32 v15, v219, v15, vcc
	v_cmp_le_i32_e32 vcc, v35, v0
	v_add_u32_e32 v35, 58, v34
	s_nop 0
	v_cndmask_b32_e32 v32, v219, v32, vcc
	v_cmp_le_i32_e32 vcc, v35, v0
	v_add_u32_e32 v35, 27, v34
	v_add_u32_e32 v34, 59, v34
	v_cndmask_b32_e32 v16, v219, v16, vcc
	v_cmp_le_i32_e32 vcc, v35, v0
	s_nop 1
	v_cndmask_b32_e32 v33, v219, v33, vcc
	v_cmp_le_i32_e32 vcc, v34, v0
	s_nop 1
	v_cndmask_b32_e32 v17, v219, v17, vcc

; #define SBAR() __builtin_amdgcn_sched_barrier(0)
; #define PKW(P, B) cvtpk_s(P[B], P[B + 1])
; template <int MODE, int THRL>
; __device__ __forceinline__ void attn_unit(const Prm& P, int b, int h, int qb, LAS char* shm, int wid) {
;     ...
;   { float sacc = pB0[0] + pB0[1];
; #pragma unroll
;     for (int r = 2; r < 16; ++r) sacc += pB0[r];
; #pragma unroll
;     for (int r = 0; r < 16; ++r) sacc += pB1[r];
;     l_reg += sacc;
;     pw0 = (u32x4){PKW(pB0, 0), PKW(pB0, 2), PKW(pB0, 4), PKW(pB0, 6)}; pw1 = (u32x4){PKW(pB0, 8), PKW(pB0, 10), PKW(pB0, 12), PKW(pB0, 14)};
;     pw2 = (u32x4){PKW(pB1, 0), PKW(pB1, 2), PKW(pB1, 4), PKW(pB1, 6)}; pw3 = (u32x4){PKW(pB1, 8), PKW(pB1, 10), PKW(pB1, 12), PKW(pB1, 14)};
;     SBAR(); pv(o, vb0 + sl_cur, PAF(0), PAF(1), PAF(2), PAF(3)); }
;     ...
;   { auto rr = __builtin_amdgcn_permlane32_swap(__float_as_uint(l_reg), __float_as_uint(l_reg), false, false); l_reg = __uint_as_float(rr[0]) + __uint_as_float(rr[1]); }
;   const long row0 = rowbase + q0 + wid * QBLK;
;   int lane_e = lane; asm volatile("" : "+v"(lane_e));
;   u32x4 ocv[4], bgv[4];
;   if (MODE == 1) {
;     const bf16_t* ocp = (const bf16_t*)(P.ws + WS_OC) + row0 * 512 + h * 64;
;     const bf16_t* bgp = (const bf16_t*)(P.ws + WS_BG) + row0 * 512 + h * 64;
; #pragma unroll
;     for (int i = 0; i < 4; ++i) { const int row = i * 8 + (lane_e >> 3), ch = lane_e & 7; ocv[i] = *(const u32x4*)(ocp + (long)row * 512 + ch * 8); bgv[i] = *(const u32x4*)(bgp + (long)row * 512 + ch * 8); }
;   }
;   if (hi == 0) { const float gte = ((const float*)(P.ws + WS_G))[(row0 + r32) * 24 + h * 3 + (MODE == 0 ? 1 : 2)]; wsf[32 + r32] = l_reg > 0.f ? gte * __builtin_amdgcn_rcpf(l_reg) : 0.f; }
.LBB0_1764:
	v_add_f32_e32 v2, v64, v65
	v_add_f32_e32 v2, v66, v2
	v_add_f32_e32 v2, v67, v2
	v_add_f32_e32 v2, v68, v2
	v_add_f32_e32 v2, v69, v2
	v_add_f32_e32 v2, v70, v2
	v_add_f32_e32 v2, v71, v2
	v_add_f32_e32 v2, v72, v2
	v_add_f32_e32 v2, v73, v2
	v_add_f32_e32 v2, v74, v2
	v_add_f32_e32 v2, v75, v2
	v_add_f32_e32 v2, v76, v2
	v_add_f32_e32 v2, v77, v2
	v_add_f32_e32 v2, v78, v2
	v_add_f32_e32 v2, v79, v2
	v_add_f32_e32 v2, v48, v2
	v_add_f32_e32 v2, v49, v2
	v_add_f32_e32 v2, v50, v2
	v_add_f32_e32 v2, v51, v2
	v_add_f32_e32 v2, v52, v2
	v_add_f32_e32 v2, v53, v2
	v_add_f32_e32 v2, v54, v2
	v_add_f32_e32 v2, v55, v2
	v_add_f32_e32 v2, v56, v2
	v_add_f32_e32 v2, v57, v2
	v_add_f32_e32 v2, v58, v2
	v_add_f32_e32 v2, v59, v2
	v_add_f32_e32 v2, v60, v2
	v_add_f32_e32 v2, v61, v2
	v_add_f32_e32 v2, v62, v2
	v_add_f32_e32 v2, v63, v2
	v_add3_u32 v14, v216, s25, v210
	v_add_f32_e32 v81, v0, v2
	v_cvt_pk_bf16_f32 v2, v64, v65
	v_cvt_pk_bf16_f32 v3, v66, v67
	v_cvt_pk_bf16_f32 v4, v68, v69
	v_cvt_pk_bf16_f32 v5, v70, v71
	v_cvt_pk_bf16_f32 v6, v72, v73
	v_cvt_pk_bf16_f32 v7, v74, v75
	v_cvt_pk_bf16_f32 v8, v76, v77
	v_cvt_pk_bf16_f32 v9, v78, v79
	v_cvt_pk_bf16_f32 v10, v48, v49
	v_cvt_pk_bf16_f32 v11, v50, v51
	v_cvt_pk_bf16_f32 v12, v52, v53
	v_cvt_pk_bf16_f32 v13, v54, v55
	v_cvt_pk_bf16_f32 v48, v56, v57
	v_cvt_pk_bf16_f32 v49, v58, v59
	v_cvt_pk_bf16_f32 v50, v60, v61
	v_cvt_pk_bf16_f32 v51, v62, v63
	v_add3_u32 v0, v14, v212, s26
	ds_read_b64_tr_b16 v[52:53],v0 offset:0
	ds_read_b64_tr_b16 v[54:55],v0 offset:512
	ds_read_b64_tr_b16 v[56:57],v0 offset:1024
	ds_read_b64_tr_b16 v[58:59],v0 offset:1536
	ds_read_b64_tr_b16 v[60:61],v0 offset:2048
	ds_read_b64_tr_b16 v[62:63],v0 offset:2560
	ds_read_b64_tr_b16 v[64:65],v0 offset:3072
	ds_read_b64_tr_b16 v[66:67],v0 offset:3584
	s_waitcnt lgkmcnt(0)
	s_nop 0
	v_mfma_f32_32x32x16_bf16 v[32:47], v[2:5], v[52:55], v[32:47]
	ds_read_b64_tr_b16 v[52:53],v0 offset:4096
	ds_read_b64_tr_b16 v[54:55],v0 offset:4608
	v_mfma_f32_32x32x16_bf16 v[32:47], v[6:9], v[56:59], v[32:47]
	ds_read_b64_tr_b16 v[56:57],v0 offset:5120
	ds_read_b64_tr_b16 v[58:59],v0 offset:5632
	v_mfma_f32_32x32x16_bf16 v[32:47], v[10:13], v[60:63], v[32:47]
	ds_read_b64_tr_b16 v[60:61],v0 offset:6144
	ds_read_b64_tr_b16 v[62:63],v0 offset:6656
	v_mfma_f32_32x32x16_bf16 v[32:47], v[48:51], v[64:67], v[32:47]
	ds_read_b64_tr_b16 v[64:65],v0 offset:7168
	ds_read_b64_tr_b16 v[66:67],v0 offset:7680
	s_waitcnt lgkmcnt(0)
	v_mfma_f32_32x32x16_bf16 v[16:31], v[2:5], v[52:55], v[16:31]
	s_lshl_b64 s[0:1], s[8:9], 1
	v_readlane_b32 s2, v251, 43
	s_add_u32 s2, s2, s0
	v_readlane_b32 s3, v251, 44
	s_addc_u32 s3, s3, s1
	s_add_u32 s2, s2, s24
	v_mov_b32_e32 v0, v208
	v_mfma_f32_32x32x16_bf16 v[16:31], v[6:9], v[56:59], v[16:31]
	s_addc_u32 s3, s3, 0
	v_readlane_b32 s6, v251, 31
	s_add_u32 s0, s6, s0
	v_readlane_b32 s6, v251, 32
	s_addc_u32 s1, s6, s1
	v_ashrrev_i32_e32 v72, 3, v0
	v_mfma_f32_32x32x16_bf16 v[16:31], v[10:13], v[60:63], v[16:31]
	v_lshlrev_b32_e32 v0, 3, v0
	s_add_u32 s0, s0, s24
	v_and_b32_e32 v0, 56, v0
	s_addc_u32 s1, s1, 0
	v_lshlrev_b32_e32 v0, 1, v0
	v_ashrrev_i32_e32 v73, 31, v72
	v_lshl_add_u64 v[2:3], s[2:3], 0, v[0:1]
	v_lshl_add_u64 v[6:7], s[0:1], 0, v[0:1]
	v_lshlrev_b64 v[4:5], 10, v[72:73]
	v_add_u32_e32 v70, 8, v72
	v_lshl_add_u64 v[8:9], v[2:3], 0, v[4:5]
	v_lshl_add_u64 v[4:5], v[6:7], 0, v[4:5]
	v_ashrrev_i32_e32 v71, 31, v70
	v_mfma_f32_32x32x16_bf16 v[16:31], v[48:51], v[64:67], v[16:31]
	global_load_dwordx4 v[60:63], v[8:9], off
	global_load_dwordx4 v[64:67], v[4:5], off
	v_lshlrev_b64 v[4:5], 10, v[70:71]
	v_add_u32_e32 v68, 16, v72
	v_lshl_add_u64 v[8:9], v[2:3], 0, v[4:5]
	v_lshl_add_u64 v[4:5], v[6:7], 0, v[4:5]
	v_ashrrev_i32_e32 v69, 31, v68
	global_load_dwordx4 v[52:55], v[8:9], off
	global_load_dwordx4 v[56:59], v[4:5], off
	v_lshlrev_b64 v[4:5], 10, v[68:69]
	v_add_u32_e32 v14, 24, v72
	v_lshl_add_u64 v[8:9], v[2:3], 0, v[4:5]
	v_lshl_add_u64 v[4:5], v[6:7], 0, v[4:5]
	v_ashrrev_i32_e32 v15, 31, v14
	global_load_dwordx4 v[10:13], v[8:9], off
	global_load_dwordx4 v[48:51], v[4:5], off
	v_lshlrev_b64 v[8:9], 10, v[14:15]
	v_lshl_add_u64 v[2:3], v[2:3], 0, v[8:9]
	v_lshl_add_u64 v[6:7], v[6:7], 0, v[8:9]
	global_load_dwordx4 v[2:5], v[2:3], off
	v_mov_b32_e32 v74, v81
	global_load_dwordx4 v[6:9], v[6:7], off
	s_nop 0
	v_permlane32_swap_b32_e32 v81, v74
	v_cmp_gt_u32_e32 vcc, 32, v208
	s_and_saveexec_b64 s[0:1], vcc
	s_cbranch_execz .LBB0_1481
	v_add_f32_e32 v76, v81, v74
	s_mul_i32 s78, s23, 12
	v_rcp_f32_e32 v75, v76
	v_cmp_lt_f32_e32 vcc, 0, v76
	s_nop 0
	v_mul_f32_e32 v74, v75, v240
	v_cndmask_b32_e32 v74, 0, v74, vcc
	v_lshl_add_u32 v75, v208, 2, s40
	ds_write_b32 v75, v74 offset:49280
	s_branch .LBB0_1481
